# group A keeps priority 2 through its softmax phase
# baseline (speedup 1.0000x reference)
; DI void diff_core(unsigned char* smem, const u16* qptr, const u16* kbase, const u16* vtbase, int vld,
;                   int ntb, int ntw, int nvalid, int ks0, const float* lut, int qpos, bool active, bool grpB,
;                   f32x16 (&O)[4], float& l_out) {
;     ...
;   auto qk = [&](int slot) {
;     if (grpB) __builtin_amdgcn_s_setprio(2); else __builtin_amdgcn_s_setprio(1);
;     const float ini = -m;
; #pragma unroll
;     for (int kb = 0; kb < 2; ++kb)
; #pragma unroll
;       for (int e = 0; e < 16; ++e) S[kb][e] = ini;
;     const LAS unsigned char* b = lds + slot * D_SLOT;
;     bf16x8 kf[4][2];
; #pragma unroll
;     for (int s = 0; s < 4; ++s)
; #pragma unroll
;       for (int kb = 0; kb < 2; ++kb) kf[s][kb] = *reinterpret_cast<const LAS bf16x8*>(b + koff[s] + kb * 32 * 256);
; #pragma unroll
;     for (int s = 0; s < 4; ++s)
; #pragma unroll
;       for (int kb = 0; kb < 2; ++kb) S[kb] = MFMA(kf[s][kb], qf[s], S[kb]);
;     __builtin_amdgcn_sched_group_barrier(0x100, 8, 0);
;     __builtin_amdgcn_sched_group_barrier(0x008, 8, 0);
;     __builtin_amdgcn_s_setprio(0);
;   };
;   auto pv = [&](int slot) {
;     if (grpB) __builtin_amdgcn_s_setprio(2); else __builtin_amdgcn_s_setprio(1);
;     const LAS unsigned char* b = lds + slot * D_SLOT;
;     bf16x8 va[4], vb[4];
; #pragma unroll
;     for (int tt = 0; tt < 4; ++tt) va[tt] = *reinterpret_cast<const LAS bf16x8*>(b + voff[0] + tt * 32 * 128);
; #pragma unroll
;     for (int tt = 0; tt < 4; ++tt) vb[tt] = *reinterpret_cast<const LAS bf16x8*>(b + voff[1] + tt * 32 * 128);
;     {
;       const bf16x8 pf = __builtin_bit_cast(bf16x8, P[0]);
; #pragma unroll
;       for (int tt = 0; tt < 4; ++tt) O[tt] = MFMA(va[tt], pf, O[tt]);
;     }
; #pragma unroll
;     for (int tt = 0; tt < 4; ++tt) va[tt] = *reinterpret_cast<const LAS bf16x8*>(b + voff[2] + tt * 32 * 128);
;     {
;       const bf16x8 pf = __builtin_bit_cast(bf16x8, P[1]);
; #pragma unroll
;       for (int tt = 0; tt < 4; ++tt) O[tt] = MFMA(vb[tt], pf, O[tt]);
;     }
; #pragma unroll
;     for (int tt = 0; tt < 4; ++tt) vb[tt] = *reinterpret_cast<const LAS bf16x8*>(b + voff[3] + tt * 32 * 128);
;     {
;       const bf16x8 pf = __builtin_bit_cast(bf16x8, P[2]);
; #pragma unroll
;       for (int tt = 0; tt < 4; ++tt) O[tt] = MFMA(va[tt], pf, O[tt]);
;     }
;     {
;       const bf16x8 pf = __builtin_bit_cast(bf16x8, P[3]);
; #pragma unroll
.LBB0_360:
	s_add_i32 s66, s64, 0x101
	s_cmp_gt_u32 s66, s16
	s_cbranch_scc1 .LBB0_362
	s_setprio 2
	s_and_b32 s0, s65, 0x18000
	v_add_u32_e32 v248, s0, v197
	ds_read_b128 v[64:67], v248 offset:16384
	ds_read_b128 v[68:71], v248 offset:20480
	ds_read_b128 v[72:75], v248 offset:24576
	ds_read_b128 v[76:79], v248 offset:28672
	s_add_i32 s67, s65, 0xfffe8000
	s_and_b32 s67, s67, 0x18000
	v_cvt_pk_bf16_f32 v144, v96, v97
	v_cvt_pk_bf16_f32 v145, v98, v99
	v_cvt_pk_bf16_f32 v146, v100, v101
	v_cvt_pk_bf16_f32 v147, v102, v103
	v_add_f32_e32 v250, v97, v96
	v_add_f32_e32 v250, v98, v250
	s_waitcnt lgkmcnt(4)
	v_mfma_f32_32x32x16_bf16 v[48:63], v[200:203], v[144:147], v[48:63]
	v_cvt_pk_bf16_f32 v148, v104, v105
	v_add_f32_e32 v250, v99, v250
	v_add_f32_e32 v250, v100, v250
	v_add_u32_e32 v249, s0, v198
	ds_read_b128 v[80:83], v249 offset:16384
	ds_read_b128 v[84:87], v249 offset:20480
	ds_read_b128 v[88:91], v249 offset:24576
	ds_read_b128 v[92:95], v249 offset:28672
	v_mfma_f32_32x32x16_bf16 v[32:47], v[204:207], v[144:147], v[32:47]
	v_cvt_pk_bf16_f32 v149, v106, v107
	v_add_f32_e32 v250, v101, v250
	v_add_f32_e32 v250, v102, v250
	v_mfma_f32_32x32x16_bf16 v[16:31], v[208:211], v[144:147], v[16:31]
	v_cvt_pk_bf16_f32 v150, v108, v109
	v_add_f32_e32 v250, v103, v250
	v_add_f32_e32 v250, v104, v250
	v_mfma_f32_32x32x16_bf16 v[0:15], v[212:215], v[144:147], v[0:15]
	v_cvt_pk_bf16_f32 v151, v110, v111
	v_add_f32_e32 v250, v105, v250
	v_add_f32_e32 v250, v106, v250
	v_mfma_f32_32x32x16_bf16 v[48:63], v[216:219], v[148:151], v[48:63]
	v_cvt_pk_bf16_f32 v152, v112, v113
	v_add_f32_e32 v250, v107, v250
	v_add_f32_e32 v250, v108, v250
	v_mfma_f32_32x32x16_bf16 v[32:47], v[220:223], v[148:151], v[32:47]
	v_cvt_pk_bf16_f32 v153, v114, v115
	v_add_f32_e32 v250, v109, v250
	v_add_f32_e32 v250, v110, v250
	v_mfma_f32_32x32x16_bf16 v[16:31], v[224:227], v[148:151], v[16:31]
	v_cvt_pk_bf16_f32 v154, v116, v117
	v_add_f32_e32 v250, v111, v250
	v_add_f32_e32 v250, v112, v250
	v_mfma_f32_32x32x16_bf16 v[0:15], v[228:231], v[148:151], v[0:15]
	v_cvt_pk_bf16_f32 v155, v118, v119
	v_add_f32_e32 v250, v113, v250
	v_add_f32_e32 v250, v114, v250
	v_add_u32_e32 v248, s67, v177
	ds_read_b128 v[200:203], v248
	ds_read_b128 v[204:207], v248 offset:8192
	v_add_u32_e32 v249, s67, v178
	ds_read_b128 v[208:211], v249
	ds_read_b128 v[212:215], v249 offset:8192
	s_waitcnt lgkmcnt(8)
	v_mfma_f32_32x32x16_bf16 v[48:63], v[64:67], v[152:155], v[48:63]
	v_cvt_pk_bf16_f32 v156, v120, v121
	v_add_f32_e32 v250, v115, v250
	v_add_f32_e32 v250, v116, v250
	v_mfma_f32_32x32x16_bf16 v[32:47], v[68:71], v[152:155], v[32:47]
	v_cvt_pk_bf16_f32 v157, v122, v123
	v_add_f32_e32 v250, v117, v250
	v_add_f32_e32 v250, v118, v250
	v_mfma_f32_32x32x16_bf16 v[16:31], v[72:75], v[152:155], v[16:31]
	v_cvt_pk_bf16_f32 v158, v124, v125
	v_add_f32_e32 v250, v119, v250
	v_add_f32_e32 v250, v120, v250
	v_mfma_f32_32x32x16_bf16 v[0:15], v[76:79], v[152:155], v[0:15]
	v_cvt_pk_bf16_f32 v159, v126, v127
	v_add_f32_e32 v250, v121, v250
	v_add_f32_e32 v250, v122, v250
	v_add_u32_e32 v248, s67, v179
	ds_read_b128 v[216:219], v248
	ds_read_b128 v[220:223], v248 offset:8192
	v_add_u32_e32 v249, s67, v180
	ds_read_b128 v[224:227], v249
	ds_read_b128 v[228:231], v249 offset:8192
	s_waitcnt lgkmcnt(8)
	v_mfma_f32_32x32x16_bf16 v[48:63], v[80:83], v[156:159], v[48:63]
	v_add_f32_e32 v250, v123, v250
	v_add_f32_e32 v250, v124, v250
	v_mfma_f32_32x32x16_bf16 v[32:47], v[84:87], v[156:159], v[32:47]
	v_add_f32_e32 v250, v125, v250
	v_add_f32_e32 v250, v126, v250
	v_mfma_f32_32x32x16_bf16 v[16:31], v[88:91], v[156:159], v[16:31]
	v_add_f32_e32 v250, v127, v250
	v_mfma_f32_32x32x16_bf16 v[0:15], v[92:95], v[156:159], v[0:15]
	v_add_f32_e32 v181, v181, v250
	s_nop 0
.LBB0_362:
	s_cmp_lt_u32 s66, s16
	s_cselect_b64 s[0:1], -1, 0
	s_cmp_ge_u32 s66, s16
	s_cbranch_scc1 .LBB0_364
	s_setprio 2
	s_waitcnt lgkmcnt(0)
	v_mfma_f32_32x32x16_bf16 v[96:111], v[200:203], v[128:131], v[232:247]
	v_mfma_f32_32x32x16_bf16 v[112:127], v[204:207], v[128:131], v[232:247]
	v_mfma_f32_32x32x16_bf16 v[96:111], v[208:211], v[132:135], v[96:111]
	v_mfma_f32_32x32x16_bf16 v[112:127], v[212:215], v[132:135], v[112:127]
	v_mfma_f32_32x32x16_bf16 v[96:111], v[216:219], v[136:139], v[96:111]
	v_mfma_f32_32x32x16_bf16 v[112:127], v[220:223], v[136:139], v[112:127]
	v_mfma_f32_32x32x16_bf16 v[96:111], v[224:227], v[140:143], v[96:111]
	v_mfma_f32_32x32x16_bf16 v[112:127], v[228:231], v[140:143], v[112:127]
	s_nop 0
